# GEMM phase prologue de-serialised: K-tile 1 stage loads issued with the K-tile 0 loads before the first wait
# baseline (speedup 1.0000x reference)
; #define PG8_STAGE(bufoff, gbase, voff) do { _Pragma("unroll") for (int _i = 0; _i < 2; ++_i) \
;         __builtin_amdgcn_global_load_lds((const unsigned*)((const char*)(gbase) + (voff)[_i]), (PG8_LAS unsigned*)(lds + (bufoff) + ldsw + _i * 8192), 16, 0, 0); } while (0)
; #define PG8_WAIT_V(n) asm volatile("s_waitcnt vmcnt(" #n ")" ::: "memory")
; #define PG8_BAR __builtin_amdgcn_s_barrier()
; template <class Epi, class Sched, bool ALIGN_EPI = false, bool SP2 = false>
; __device__ __forceinline__ void gemm_phase(PG8_LAS unsigned char* lds, const Gemm g, const Sched& S, const Epi& E) {
;     ...
;     for (int i = 0; i < 2; ++i) { int R, C; stage_rc(tid * 16 + i * 8192, R, C); const int Rb = Epi::PERM ? ((R & ~31) + perm32(R & 31)) : R;
;         voffA[i] = (unsigned)(R * K + C) * 2u; voffB[i] = (unsigned)(Rb * K + C) * 2u; }
;     const size_t kstep = (size_t)(BK * 2);
;     const size_t hstep = (size_t)HALF * K * 2;
;     const size_t tstep = 2 * hstep;
;     const unsigned ldsw = (unsigned)wid * 1024u;
;     const int aoff = lds_byte(wr * 64 + fr, fq * 8), boff = lds_byte(wc * 32 + fr, fq * 8);
;     ...
;         PG8_STAGE(PG8_SB(0, 0), cB, voffB); PG8_STAGE(PG8_SB(0, 1), cB + hstep, voffB); PG8_STAGE(PG8_SA(0, 0), cA, voffA); PG8_STAGE(PG8_SA(0, 1), cA + hstep, voffA);
;         if (wr == 1) PG8_BAR;
;         PG8_WAIT_V(2); PG8_BAR;
;         PG8_STAGE(PG8_SB(1, 0), cB + kstep, voffB); PG8_STAGE(PG8_SA(1, 0), cA + kstep, voffA); PG8_STAGE(PG8_SB(1, 1), cB + hstep + kstep, voffB);
;         PG8_WAIT_V(6); PG8_BAR;
.LBB0_698:
	s_andn2_b64 vcc, exec, s[2:3]
	s_cbranch_vccnz .LBB0_770
	s_waitcnt vmcnt(3)
	v_bfe_i32 v4, v0, 27, 1
	v_lshlrev_b32_e32 v2, 4, v0
	v_lshrrev_b32_e32 v4, 22, v4
	v_add_u32_e32 v4, v2, v4
	v_and_b32_e32 v4, 0xfffffc00, v4
	v_ashrrev_i32_e32 v3, 31, v0
	v_sub_u32_e32 v4, v2, v4
	v_lshrrev_b32_e32 v3, 26, v3
	v_lshrrev_b32_e32 v5, 4, v4
	v_add_u32_e32 v3, v0, v3
	v_bitop3_b32 v5, v5, v4, 32 bitop3:0x6c
	v_ashrrev_i32_e32 v4, 31, v4
	v_ashrrev_i32_e32 v3, 6, v3
	v_lshrrev_b32_e32 v4, 26, v4
	v_lshlrev_b32_e32 v6, 3, v3
	v_add_u32_e32 v4, v5, v4
	v_and_b32_e32 v6, -16, v6
	v_ashrrev_i32_e32 v4, 6, v4
	v_lshlrev_b32_e32 v3, 5, v3
	v_add_u32_e32 v6, v4, v6
	s_waitcnt vmcnt(1)
	v_and_b32_e32 v14, 32, v3
	v_mul_i32_i24_e32 v3, 64, v4
	v_sub_u32_e32 v3, v5, v3
	v_lshlrev_b32_e32 v5, 1, v6
	v_lshrrev_b32_e32 v7, 2, v6
	v_and_b32_e32 v4, 3, v4
	s_mov_b32 s2, 0x7fffffe0
	v_ashrrev_i16_sdwa v3, v223, sext(v3) dst_sel:DWORD dst_unused:UNUSED_PAD src0_sel:DWORD src1_sel:BYTE_0
	v_and_b32_e32 v5, 24, v5
	v_and_b32_e32 v7, 4, v7
	v_and_or_b32 v4, v6, s2, v4
	v_bfe_i32 v15, v3, 0, 16
	v_or3_b32 v4, v4, v7, v5
	v_add_u32_e32 v3, v14, v15
	s_waitcnt vmcnt(0)
	v_mul_lo_u32 v16, v6, s11
	v_mul_lo_u32 v4, v4, s11
	v_add_u32_e32 v2, 0x2000, v2
	v_add_lshl_u32 v166, v3, v16, 1
	v_add_lshl_u32 v168, v4, v3, 1
	v_ashrrev_i32_e32 v3, 31, v2
	v_lshrrev_b32_e32 v3, 22, v3
	v_add_u32_e32 v3, v2, v3
	v_ashrrev_i32_e32 v3, 10, v3
	v_mul_i32_i24_e32 v4, 0x400, v3
	v_sub_u32_e32 v2, v2, v4
	v_lshrrev_b32_e32 v4, 4, v2
	v_bitop3_b32 v2, v4, v2, 32 bitop3:0x6c
	v_ashrrev_i32_e32 v5, 31, v2
	v_lshrrev_b32_e32 v5, 26, v5
	v_lshlrev_b32_e32 v4, 3, v3
	v_add_u32_e32 v5, v2, v5
	v_and_b32_e32 v4, -16, v4
	v_ashrrev_i32_e32 v6, 6, v5
	v_add_u32_e32 v4, v6, v4
	v_and_b32_e32 v6, 3, v6
	s_lshl_b32 s96, s11, 8
	v_and_or_b32 v6, v4, s2, v6
	s_lshl_b64 s[30:31], s[96:97], 1
	s_ashr_i32 s2, s67, 31
	s_mul_i32 s2, s30, s2
	s_mul_hi_u32 s3, s30, s67
	s_add_i32 s2, s3, s2
	s_bfe_u32 s3, s11, 0x10017
	s_mul_i32 s6, s3, s67
	s_add_i32 s24, s2, s6
	s_ashr_i32 s2, s63, 31
	s_mul_i32 s2, s30, s2
	s_mul_hi_u32 s6, s30, s63
	s_ashr_i32 s9, s8, 6
	v_lshlrev_b32_e32 v3, 5, v3
	s_add_i32 s2, s6, s2
	s_mul_i32 s3, s3, s63
	v_and_b32_e32 v17, 32, v3
	v_and_b32_e32 v3, 0xc0, v5
	s_ashr_i32 s21, s8, 8
	s_lshl_b32 s22, s9, 10
	s_add_i32 s2, s2, s3
	s_mul_i32 s3, s30, s63
	v_sub_u32_e32 v2, v2, v3
	v_lshlrev_b32_e32 v3, 1, v4
	v_lshrrev_b32_e32 v5, 2, v4
	s_add_u32 s6, s38, s3
	v_ashrrev_i16_sdwa v2, v223, sext(v2) dst_sel:DWORD dst_unused:UNUSED_PAD src0_sel:DWORD src1_sel:BYTE_0
	v_and_b32_e32 v3, 24, v3
	v_and_b32_e32 v5, 4, v5
	s_addc_u32 s7, s39, s2
	s_add_i32 s23, s22, 0
	v_bfe_i32 v18, v2, 0, 16
	v_or3_b32 v3, v6, v5, v3
	s_add_i32 m0, s23, 0x10000
	v_add_u32_e32 v2, v17, v18
	v_mul_lo_u32 v3, v3, s11
	global_load_lds_dwordx4 v168, s[6:7]
	s_add_i32 m0, s23, 0x12000
	v_add_lshl_u32 v172, v3, v2, 1
	s_add_u32 s2, s6, s96
	global_load_lds_dwordx4 v172, s[6:7]
	s_addc_u32 s3, s7, 0
	s_add_i32 m0, s23, 0x14000
	s_mul_i32 s25, s30, s67
	v_mov_b32_e32 v169, v1
	v_mov_b32_e32 v173, v1
	global_load_lds_dwordx4 v168, s[2:3]
	s_add_i32 m0, s23, 0x16000
	v_lshl_add_u64 v[6:7], s[2:3], 0, v[168:169]
	v_lshl_add_u64 v[8:9], s[2:3], 0, v[172:173]
	global_load_lds_dwordx4 v172, s[2:3]
	s_add_u32 s2, s34, s25
	s_addc_u32 s3, s35, s24
	s_add_i32 s24, s23, 0x2000
	v_mul_lo_u32 v19, v4, s11
	s_mov_b32 m0, s23
	s_add_u32 s36, s2, s96
	v_add_lshl_u32 v170, v2, v19, 1
	global_load_lds_dwordx4 v166, s[2:3]
	s_mov_b32 m0, s24
	s_addc_u32 s37, s3, 0
	s_add_i32 s25, s23, 0x4000
	global_load_lds_dwordx4 v170, s[2:3]
	s_mov_b32 m0, s25
	s_add_i32 s27, s23, 0x6000
	global_load_lds_dwordx4 v166, s[36:37]
	s_mov_b32 m0, s27
	v_mov_b32_e32 v167, v1
	global_load_lds_dwordx4 v170, s[36:37]
	v_mov_b32_e32 v171, v1
	s_cmp_eq_u32 s21, 1
	v_lshl_add_u64 v[2:3], s[6:7], 0, v[168:169]
	v_lshl_add_u64 v[4:5], s[6:7], 0, v[172:173]
	v_lshl_add_u64 v[10:11], s[2:3], 0, v[166:167]
	v_lshl_add_u64 v[12:13], s[2:3], 0, v[170:171]
	s_cselect_b64 s[36:37], -1, 0
	s_add_i32 m0, s23, 0x18000
	v_lshl_add_u64 v[2:3], v[2:3], 0, s[12:13]
	global_load_lds_dwordx4 v[2:3], off
	v_lshl_add_u64 v[2:3], v[4:5], 0, s[12:13]
	s_add_i32 m0, s23, 0x1a000
	s_add_i32 s54, s23, 0x8000
	global_load_lds_dwordx4 v[2:3], off
	v_lshl_add_u64 v[2:3], v[10:11], 0, s[12:13]
	s_mov_b32 m0, s54
	s_add_i32 s55, s23, 0xa000
	global_load_lds_dwordx4 v[2:3], off
	v_lshl_add_u64 v[2:3], v[12:13], 0, s[12:13]
	s_mov_b32 m0, s55
	s_lshl_b32 s9, s9, 5
	global_load_lds_dwordx4 v[2:3], off
	s_add_i32 m0, s23, 0x1c000
	v_lshl_add_u64 v[2:3], v[6:7], 0, s[12:13]
	global_load_lds_dwordx4 v[2:3], off
	v_lshl_add_u64 v[2:3], v[8:9], 0, s[12:13]
	s_add_i32 m0, s23, 0x1e000
	s_lshr_b32 s56, s11, 6
	global_load_lds_dwordx4 v[2:3], off
	s_cmp_lg_u32 s21, 1
	s_cbranch_scc1 .LBB0_701
	s_barrier
.LBB0_701:
	s_waitcnt vmcnt(8)
	s_barrier
	v_lshrrev_b32_e32 v2, 1, v0
	v_and_b32_e32 v2, 24, v2
	v_and_b32_e32 v3, 15, v0
	v_lshlrev_b32_e32 v4, 1, v2
	v_lshlrev_b32_e32 v0, 2, v0
	v_lshl_or_b32 v4, v3, 6, v4
	s_lshl_b32 s11, s21, 13
	v_and_b32_e32 v0, 32, v0
	s_and_b32 s9, s9, 0x60
	v_bitop3_b32 v5, v4, s11, v0 bitop3:0xde
	s_lshl_b32 s11, s9, 7
	s_add_i32 s57, s56, -2
	s_cmpk_lt_u32 s8, 0x100
	s_cselect_b64 s[40:41], -1, 0
	s_lshl_b32 s58, s10, 3
	v_bitop3_b32 v211, v4, s11, v0 bitop3:0xde
	v_cvt_f32_u32_e32 v0, s58
	s_sub_i32 s8, 0, s58
	s_waitcnt vmcnt(6)
	v_lshl_or_b32 v210, s21, 6, v3
	v_rcp_iflag_f32_e32 v0, v0
	s_mov_b32 s59, 0
	v_cmp_eq_u32_e64 s[42:43], 0, v3
	s_ashr_i32 s60, s20, 31
	v_mul_f32_e32 v0, 0x4f7ffffe, v0
	v_cvt_u32_f32_e32 v0, v0
	s_mov_b32 s29, s97
	s_lshr_b32 s61, s28, 3
	v_or_b32_e32 v212, s9, v2
	v_readfirstlane_b32 s10, v0
	v_add_u32_e32 v0, v16, v14
	v_add_lshl_u32 v0, v0, v15, 1
	s_mul_i32 s8, s8, s10
	v_lshl_add_u64 v[174:175], s[96:97], 0, v[0:1]
	v_add_u32_e32 v0, v19, v17
	s_mul_hi_u32 s8, s10, s8
	v_add_lshl_u32 v0, v0, v18, 1
	s_add_i32 s62, s10, s8
	v_lshl_add_u64 v[176:177], s[96:97], 0, v[0:1]
	v_add_u32_e32 v214, 0, v5
	s_lshl_b32 s64, s9, 1
	v_lshlrev_b32_e32 v178, 1, v2
	s_barrier
	s_branch .LBB0_704
